# adds phase8 score-fragment loads issued up front with counted vmcnt (on top of the three de-serialised epilogues)
# speedup vs baseline: 1.0402x; 1.0041x over previous
.LBB0_1688:
	s_cmpk_gt_i32 s37, 0x80f
	s_cbranch_scc1 .LBB0_1687
	s_and_b32 s2, s38, 0xffffff80
	v_mbcnt_lo_u32_b32 v69, -1, 0
	v_mbcnt_hi_u32_b32 v69, -1, v69
	s_or_b32 s2, s2, s13
	v_and_b32_e32 v2, 31, v69
	v_or_b32_e32 v0, s2, v2
	v_ashrrev_i32_e32 v1, 31, v0
	s_and_b32 s11, s37, 7
	v_lshlrev_b64 v[0:1], 11, v[0:1]
	v_lshl_add_u64 v[0:1], s[4:5], 0, v[0:1]
	s_lshl_b32 s2, s11, 8
	v_lshl_add_u64 v[4:5], v[0:1], 0, s[2:3]
	s_lshl_b32 s2, s11, 1
	v_ashrrev_i32_e32 v102, 5, v69
	s_add_i32 s2, s2, s1
	s_lshl_b64 s[14:15], s[2:3], 14
	v_lshlrev_b32_e32 v0, 3, v102
	v_ashrrev_i32_e32 v1, 31, v0
	s_add_u32 s14, s17, s14
	s_waitcnt lgkmcnt(8)
	v_lshlrev_b64 v[6:7], 1, v[0:1]
	s_addc_u32 s15, s18, s15
	v_lshl_add_u64 v[0:1], s[14:15], 0, v[6:7]
	v_lshlrev_b32_e32 v64, 7, v2
	v_lshl_add_u64 v[94:95], v[0:1], 0, v[64:65]
	s_mov_b32 s11, s3
	v_lshl_add_u64 v[4:5], v[4:5], 0, s[10:11]
	v_lshl_add_u64 v[96:97], v[4:5], 0, v[6:7]
	v_add_co_u32_e32 v98, vcc, s28, v94
	s_nop 1
	v_addc_co_u32_e32 v99, vcc, 0, v95, vcc
	v_add_co_u32_e32 v90, vcc, s29, v94
	s_nop 1
	v_addc_co_u32_e32 v91, vcc, 0, v95, vcc
	v_add_co_u32_e32 v100, vcc, s27, v94
	s_nop 1
	v_addc_co_u32_e32 v101, vcc, 0, v95, vcc
	global_load_dwordx4 v[104:107], v[94:95], off
	global_load_dwordx4 v[108:111], v[96:97], off
	global_load_dwordx4 v[112:115], v[96:97], off offset:32
	global_load_dwordx4 v[116:119], v[94:95], off offset:32
	global_load_dwordx4 v[120:123], v[98:99], off offset:-4096
	global_load_dwordx4 v[124:127], v[90:91], off offset:96
	global_load_dwordx4 v[128:131], v[98:99], off
	global_load_dwordx4 v[132:135], v[98:99], off offset:32
	global_load_dwordx4 v[136:139], v[90:91], off
	global_load_dwordx4 v[140:143], v[100:101], off offset:32
	global_load_dwordx4 v[144:147], v[100:101], off offset:64
	global_load_dwordx4 v[148:151], v[90:91], off offset:32
	global_load_dwordx4 v[152:155], v[94:95], off offset:64
	global_load_dwordx4 v[156:159], v[90:91], off offset:64
	global_load_dwordx4 v[160:163], v[96:97], off offset:64
	global_load_dwordx4 v[164:167], v[96:97], off offset:96
	global_load_dwordx4 v[168:171], v[94:95], off offset:96
	global_load_dwordx4 v[172:175], v[98:99], off offset:64
	global_load_dwordx4 v[176:179], v[98:99], off offset:96
	global_load_dwordx4 v[180:183], v[100:101], off offset:96
	v_lshlrev_b32_e32 v64, 2, v102
	s_nop 0
	s_waitcnt vmcnt(18)
	v_mfma_f32_32x32x16_bf16 v[32:47], v[104:107], v[108:111], 0
	s_nop 1
	s_waitcnt vmcnt(16)
	v_mfma_f32_32x32x16_bf16 v[32:47], v[116:119], v[112:115], v[32:47]
	v_cmp_lt_i32_e32 vcc, v67, v68
	s_waitcnt vmcnt(15)
	v_mfma_f32_32x32x16_bf16 v[48:63], v[120:123], v[108:111], 0
	s_waitcnt lgkmcnt(1)
	s_waitcnt vmcnt(13)
	v_mfma_f32_32x32x16_bf16 v[16:31], v[128:131], v[108:111], 0
	s_waitcnt vmcnt(12)
	v_mfma_f32_32x32x16_bf16 v[16:31], v[132:135], v[112:115], v[16:31]
	s_waitcnt vmcnt(10)
	v_mfma_f32_32x32x16_bf16 v[48:63], v[140:143], v[112:115], v[48:63]
	s_nop 0
	s_waitcnt lgkmcnt(0)
	v_mfma_f32_32x32x16_bf16 v[0:15], v[136:139], v[108:111], 0
	s_waitcnt vmcnt(8)
	v_mfma_f32_32x32x16_bf16 v[0:15], v[148:151], v[112:115], v[0:15]
	s_nop 0
	s_waitcnt vmcnt(5)
	v_mfma_f32_32x32x16_bf16 v[32:47], v[152:155], v[160:163], v[32:47]
	v_mfma_f32_32x32x16_bf16 v[48:63], v[144:147], v[160:163], v[48:63]
	v_add_u32_e32 v98, 51, v64
	v_add_u32_e32 v99, 56, v64
	v_mfma_f32_32x32x16_bf16 v[0:15], v[156:159], v[160:163], v[0:15]
	v_add_u32_e32 v90, 16, v64
	v_add_u32_e32 v91, 17, v64
	v_add_u32_e32 v92, 18, v64
	v_add_u32_e32 v93, 19, v64
	s_waitcnt vmcnt(3)
	v_mfma_f32_32x32x16_bf16 v[32:47], v[168:171], v[164:167], v[32:47]
	v_add_u32_e32 v94, 32, v64
	v_add_u32_e32 v95, 40, v64
	v_add_u32_e32 v96, 41, v64
	v_add_u32_e32 v97, 50, v64
	v_mfma_f32_32x32x16_bf16 v[0:15], v[124:127], v[164:167], v[0:15]
	s_nop 6
	v_and_b32_e32 v33, 0xffffff80, v33
	v_and_or_b32 v32, v32, s26, v64
	v_and_b32_e32 v34, 0xffffff80, v34
	v_and_b32_e32 v35, 0xffffff80, v35
	v_or3_b32 v33, v64, v33, 1
	v_or3_b32 v34, v64, v34, 2
	v_or3_b32 v35, v64, v35, 3
	v_and_or_b32 v40, v40, s26, v90
	v_and_or_b32 v41, v41, s26, v91
	v_and_or_b32 v42, v42, s26, v92
	v_and_or_b32 v43, v43, s26, v93
	s_waitcnt vmcnt(2)
	v_mfma_f32_32x32x16_bf16 v[16:31], v[172:175], v[160:163], v[16:31]
	v_add_u32_e32 v82, 8, v64
	v_add_u32_e32 v83, 9, v64
	v_and_or_b32 v36, v36, s26, v82
	v_add_u32_e32 v84, 10, v64
	v_and_or_b32 v37, v37, s26, v83
	v_add_u32_e32 v85, 11, v64
	s_waitcnt vmcnt(1)
	v_mfma_f32_32x32x16_bf16 v[16:31], v[176:179], v[164:167], v[16:31]
	v_and_or_b32 v38, v38, s26, v84
	v_and_or_b32 v39, v39, s26, v85
	v_add_u32_e32 v86, 42, v64
	v_add_u32_e32 v87, 43, v64
	v_add_u32_e32 v88, 48, v64
	v_add_u32_e32 v89, 49, v64
	s_waitcnt vmcnt(0)
	v_mfma_f32_32x32x16_bf16 v[48:63], v[180:183], v[164:167], v[48:63]
	v_add_u32_e32 v70, 24, v64
	v_and_or_b32 v44, v44, s26, v70
	v_add_u32_e32 v70, 57, v64
	v_add_u32_e32 v71, 25, v64
	v_add_u32_e32 v72, 26, v64
	v_and_or_b32 v45, v45, s26, v71
	v_add_u32_e32 v73, 27, v64
	s_nop 4
	v_and_or_b32 v61, v61, s26, v70
	v_add_u32_e32 v70, 58, v64
	v_and_or_b32 v62, v62, s26, v70
	v_add_u32_e32 v70, 59, v64
	v_and_or_b32 v63, v63, s26, v70
	v_add_u32_e32 v70, 64, v64
	v_and_or_b32 v71, v16, s26, v70
	v_and_b32_e32 v16, 0xffffff80, v17
	v_and_or_b32 v46, v46, s26, v72
	v_or3_b32 v72, v70, v16, 1
	v_and_b32_e32 v16, 0xffffff80, v18
	v_and_or_b32 v47, v47, s26, v73
	v_or3_b32 v73, v70, v16, 2
	v_and_b32_e32 v16, 0xffffff80, v19
	v_or3_b32 v70, v70, v16, 3
	v_add_u32_e32 v16, 0x48, v64
	v_and_or_b32 v74, v20, s26, v16
	v_add_u32_e32 v16, 0x49, v64
	v_and_or_b32 v75, v21, s26, v16
	v_add_u32_e32 v16, 0x4a, v64
	v_and_or_b32 v76, v22, s26, v16
	v_add_u32_e32 v16, 0x4b, v64
	v_and_or_b32 v77, v23, s26, v16
	v_add_u32_e32 v16, 0x50, v64
	v_and_or_b32 v78, v24, s26, v16
	v_add_u32_e32 v16, 0x51, v64
	v_and_or_b32 v79, v25, s26, v16
	v_add_u32_e32 v16, 0x52, v64
	v_and_or_b32 v80, v26, s26, v16
	v_add_u32_e32 v16, 0x53, v64
	v_and_or_b32 v81, v27, s26, v16
	v_add_u32_e32 v16, 0x58, v64
	v_and_or_b32 v82, v28, s26, v16
	v_add_u32_e32 v16, 0x59, v64
	v_and_or_b32 v83, v29, s26, v16
	v_add_u32_e32 v16, 0x5a, v64
	v_and_or_b32 v84, v30, s26, v16
	v_add_u32_e32 v16, 0x5b, v64
	v_add_u32_e32 v18, 0x60, v64
	v_and_or_b32 v85, v31, s26, v16
	v_and_or_b32 v16, v0, s26, v18
	v_and_b32_e32 v0, 0xffffff80, v1
	v_or3_b32 v17, v18, v0, 1
	v_and_b32_e32 v0, 0xffffff80, v2
	v_and_b32_e32 v1, 0xffffff80, v3
	v_or3_b32 v0, v18, v0, 2
	v_or3_b32 v18, v18, v1, 3
	v_add_u32_e32 v1, 0x68, v64
	v_add_u32_e32 v2, 0x69, v64
	v_add_u32_e32 v3, 0x6b, v64
	v_and_or_b32 v1, v4, s26, v1
	v_and_or_b32 v19, v5, s26, v2
	v_add_u32_e32 v2, 0x6a, v64
	v_and_or_b32 v7, v7, s26, v3
	v_add_u32_e32 v3, 0x70, v64
	v_add_u32_e32 v4, 0x71, v64
	v_add_u32_e32 v5, 0x73, v64
	v_and_or_b32 v2, v6, s26, v2
	v_and_or_b32 v3, v8, s26, v3
	v_and_or_b32 v8, v9, s26, v4
	v_add_u32_e32 v4, 0x72, v64
	v_and_or_b32 v9, v11, s26, v5
	v_add_u32_e32 v5, 0x78, v64
	v_add_u32_e32 v6, 0x79, v64
	v_and_or_b32 v4, v10, s26, v4
	v_and_or_b32 v5, v12, s26, v5
	v_and_or_b32 v10, v13, s26, v6
	v_add_u32_e32 v6, 0x7a, v64
	v_add_u32_e32 v11, 0x7b, v64
	v_max_f32_e32 v12, v32, v32
	v_max_f32_e32 v13, v33, v33
	v_and_or_b32 v6, v14, s26, v6
	v_and_or_b32 v11, v15, s26, v11
	v_min_f32_e32 v14, v12, v13
	v_max_f32_e32 v12, v12, v13
	v_max_f32_e32 v13, v35, v35
	v_max_f32_e32 v15, v34, v34
	v_and_b32_e32 v49, 0xffffff80, v49
	v_max_f32_e32 v20, v15, v13
	v_min_f32_e32 v13, v15, v13
	v_max_f32_e32 v15, v37, v37
	v_max_f32_e32 v21, v36, v36
	v_and_or_b32 v48, v48, s26, v94
	v_and_b32_e32 v50, 0xffffff80, v50
	v_and_b32_e32 v51, 0xffffff80, v51
	v_or3_b32 v49, v94, v49, 1
	v_min_f32_e32 v22, v21, v15
	v_max_f32_e32 v15, v21, v15
	v_max_f32_e32 v21, v39, v39
	v_max_f32_e32 v23, v38, v38
	v_or3_b32 v50, v94, v50, 2
	v_or3_b32 v51, v94, v51, 3
	v_max_f32_e32 v24, v23, v21
	v_min_f32_e32 v21, v23, v21
	v_max_f32_e32 v23, v41, v41
	v_max_f32_e32 v25, v40, v40
	v_max_f32_e32 v40, v48, v48
	v_max_f32_e32 v41, v49, v49
	v_max_f32_e32 v64, v71, v71
	v_max_f32_e32 v71, v72, v72
	v_and_or_b32 v52, v52, s26, v95
	v_and_or_b32 v53, v53, s26, v96
	v_min_f32_e32 v26, v25, v23
	v_max_f32_e32 v23, v25, v23
	v_max_f32_e32 v25, v43, v43
	v_max_f32_e32 v27, v42, v42
	v_min_f32_e32 v42, v40, v41
	v_max_f32_e32 v40, v40, v41
	v_max_f32_e32 v41, v51, v51
	v_max_f32_e32 v43, v50, v50
	v_min_f32_e32 v72, v64, v71
	v_max_f32_e32 v64, v64, v71
	v_max_f32_e32 v70, v70, v70
	v_max_f32_e32 v71, v73, v73
	v_max_f32_e32 v16, v16, v16
	v_max_f32_e32 v17, v17, v17
	v_and_or_b32 v54, v54, s26, v86
	v_and_or_b32 v55, v55, s26, v87
	v_max_f32_e32 v28, v27, v25
	v_min_f32_e32 v25, v27, v25
	v_max_f32_e32 v27, v45, v45
	v_max_f32_e32 v29, v44, v44
	v_max_f32_e32 v44, v43, v41
	v_min_f32_e32 v41, v43, v41
	v_max_f32_e32 v43, v53, v53
	v_max_f32_e32 v45, v52, v52
	v_max_f32_e32 v73, v71, v70
	v_min_f32_e32 v70, v71, v70
	v_max_f32_e32 v71, v75, v75
	v_max_f32_e32 v74, v74, v74
	v_min_f32_e32 v93, v16, v17
	v_max_f32_e32 v16, v16, v17
	v_max_f32_e32 v17, v18, v18
	v_max_f32_e32 v0, v0, v0
	v_and_or_b32 v56, v56, s26, v88
	v_and_or_b32 v57, v57, s26, v89
	v_min_f32_e32 v30, v29, v27
	v_max_f32_e32 v27, v29, v27
	v_max_f32_e32 v29, v47, v47
	v_max_f32_e32 v31, v46, v46
	v_min_f32_e32 v46, v45, v43
	v_max_f32_e32 v43, v45, v43
	v_max_f32_e32 v45, v55, v55
	v_max_f32_e32 v47, v54, v54
	v_min_f32_e32 v75, v74, v71
	v_max_f32_e32 v71, v74, v71
	v_max_f32_e32 v74, v77, v77
	v_max_f32_e32 v76, v76, v76
	v_max_f32_e32 v18, v0, v17
	v_min_f32_e32 v0, v0, v17
	v_max_f32_e32 v17, v19, v19
	v_max_f32_e32 v1, v1, v1
	v_max_f32_e32 v7, v7, v7
	v_max_f32_e32 v2, v2, v2
	v_and_or_b32 v58, v58, s26, v97
	v_and_or_b32 v59, v59, s26, v98
	v_max_f32_e32 v48, v47, v45
	v_min_f32_e32 v45, v47, v45
	v_max_f32_e32 v47, v57, v57
	v_max_f32_e32 v49, v56, v56
	v_max_f32_e32 v77, v76, v74
	v_min_f32_e32 v74, v76, v74
	v_max_f32_e32 v76, v79, v79
	v_max_f32_e32 v78, v78, v78
	v_min_f32_e32 v19, v1, v17
	v_max_f32_e32 v1, v1, v17
	v_max_f32_e32 v17, v2, v7
	v_min_f32_e32 v2, v2, v7
	v_max_f32_e32 v7, v8, v8
	v_max_f32_e32 v3, v3, v3
	v_and_or_b32 v60, v60, s26, v99
	v_min_f32_e32 v50, v49, v47
	v_max_f32_e32 v47, v49, v47
	v_max_f32_e32 v49, v59, v59
	v_max_f32_e32 v51, v58, v58
	v_min_f32_e32 v79, v78, v76
	v_max_f32_e32 v76, v78, v76
	v_max_f32_e32 v78, v81, v81
	v_max_f32_e32 v80, v80, v80
	v_min_f32_e32 v8, v3, v7
	v_max_f32_e32 v3, v3, v7
	v_max_f32_e32 v7, v9, v9
	v_max_f32_e32 v4, v4, v4
	v_max_f32_e32 v52, v51, v49
	v_min_f32_e32 v49, v51, v49
	v_max_f32_e32 v51, v61, v61
	v_max_f32_e32 v53, v60, v60
	v_max_f32_e32 v81, v80, v78
	v_min_f32_e32 v78, v80, v78
	v_max_f32_e32 v80, v83, v83
	v_max_f32_e32 v82, v82, v82
	v_max_f32_e32 v9, v4, v7
	v_min_f32_e32 v4, v4, v7
	v_max_f32_e32 v7, v10, v10
	v_max_f32_e32 v5, v5, v5
	v_min_f32_e32 v54, v53, v51
	v_max_f32_e32 v51, v53, v51
	v_max_f32_e32 v53, v63, v63
	v_max_f32_e32 v55, v62, v62
	v_min_f32_e32 v83, v82, v80
	v_max_f32_e32 v80, v82, v80
	v_max_f32_e32 v82, v85, v85
	v_max_f32_e32 v84, v84, v84
	v_min_f32_e32 v10, v5, v7
	v_max_f32_e32 v5, v5, v7
	v_max_f32_e32 v7, v11, v11
	v_max_f32_e32 v6, v6, v6
	v_max_f32_e32 v32, v31, v29
	v_min_f32_e32 v29, v31, v29
	v_max_f32_e32 v56, v55, v53
	v_min_f32_e32 v53, v55, v53
	v_max_f32_e32 v85, v84, v82
	v_min_f32_e32 v82, v84, v82
	v_max_f32_e32 v11, v6, v7
	v_min_f32_e32 v6, v6, v7
	v_min_f32_e32 v31, v12, v13
	v_max_f32_e32 v12, v12, v13
	v_min_f32_e32 v13, v14, v20
	v_max_f32_e32 v14, v14, v20
	v_max_f32_e32 v20, v15, v21
	v_min_f32_e32 v15, v15, v21
	v_max_f32_e32 v21, v22, v24
	v_min_f32_e32 v22, v22, v24
	v_min_f32_e32 v24, v23, v25
	v_max_f32_e32 v23, v23, v25
	v_min_f32_e32 v25, v26, v28
	v_max_f32_e32 v26, v26, v28
	v_max_f32_e32 v28, v27, v29
	v_min_f32_e32 v27, v27, v29
	v_max_f32_e32 v29, v30, v32
	v_min_f32_e32 v30, v30, v32
	v_min_f32_e32 v55, v40, v41
	v_max_f32_e32 v40, v40, v41
	v_min_f32_e32 v41, v42, v44
	v_max_f32_e32 v42, v42, v44
	v_max_f32_e32 v44, v43, v45
	v_min_f32_e32 v43, v43, v45
	v_max_f32_e32 v45, v46, v48
	v_min_f32_e32 v46, v46, v48
	v_min_f32_e32 v48, v47, v49
	v_max_f32_e32 v47, v47, v49
	v_min_f32_e32 v49, v50, v52
	v_max_f32_e32 v50, v50, v52
	v_max_f32_e32 v52, v51, v53
	v_min_f32_e32 v51, v51, v53
	v_max_f32_e32 v53, v54, v56
	v_min_f32_e32 v54, v54, v56
	v_min_f32_e32 v84, v64, v70
	v_max_f32_e32 v64, v64, v70
	v_min_f32_e32 v70, v72, v73
	v_max_f32_e32 v72, v72, v73
	v_max_f32_e32 v73, v71, v74
	v_min_f32_e32 v71, v71, v74
	v_max_f32_e32 v74, v75, v77
	v_min_f32_e32 v75, v75, v77
	v_min_f32_e32 v77, v76, v78
	v_max_f32_e32 v76, v76, v78
	v_min_f32_e32 v78, v79, v81
	v_max_f32_e32 v79, v79, v81
	v_max_f32_e32 v81, v80, v82
	v_min_f32_e32 v80, v80, v82
	v_max_f32_e32 v82, v83, v85
	v_min_f32_e32 v83, v83, v85
	v_min_f32_e32 v7, v16, v0
	v_max_f32_e32 v0, v16, v0
	v_min_f32_e32 v16, v93, v18
	v_max_f32_e32 v18, v93, v18
	v_max_f32_e32 v93, v1, v2
	v_min_f32_e32 v1, v1, v2
	v_max_f32_e32 v2, v19, v17
	v_min_f32_e32 v17, v19, v17
	v_min_f32_e32 v19, v3, v4
	v_max_f32_e32 v3, v3, v4
	v_min_f32_e32 v4, v8, v9
	v_max_f32_e32 v8, v8, v9
	v_max_f32_e32 v9, v5, v6
	v_min_f32_e32 v5, v5, v6
	v_max_f32_e32 v6, v10, v11
	v_min_f32_e32 v10, v10, v11
	v_min_f32_e32 v32, v12, v14
	v_max_f32_e32 v12, v12, v14
	v_min_f32_e32 v14, v31, v13
	v_max_f32_e32 v13, v31, v13
	v_max_f32_e32 v31, v15, v22
	v_min_f32_e32 v15, v15, v22
	v_max_f32_e32 v22, v20, v21
	v_min_f32_e32 v20, v20, v21
	v_min_f32_e32 v21, v23, v26
	v_max_f32_e32 v23, v23, v26
	v_min_f32_e32 v26, v24, v25
	v_max_f32_e32 v24, v24, v25
	v_max_f32_e32 v25, v27, v30
	v_min_f32_e32 v27, v27, v30
	v_max_f32_e32 v30, v28, v29
	v_min_f32_e32 v28, v28, v29
	v_min_f32_e32 v56, v40, v42
	v_max_f32_e32 v40, v40, v42
	v_min_f32_e32 v42, v55, v41
	v_max_f32_e32 v41, v55, v41
	v_max_f32_e32 v55, v43, v46
	v_min_f32_e32 v43, v43, v46
	v_max_f32_e32 v46, v44, v45
	v_min_f32_e32 v44, v44, v45
	v_min_f32_e32 v45, v47, v50
	v_max_f32_e32 v47, v47, v50
	v_min_f32_e32 v50, v48, v49
	v_max_f32_e32 v48, v48, v49
	v_max_f32_e32 v49, v51, v54
	v_min_f32_e32 v51, v51, v54
	v_max_f32_e32 v54, v52, v53
	v_min_f32_e32 v52, v52, v53
	v_min_f32_e32 v85, v64, v72
	v_max_f32_e32 v64, v64, v72
	v_min_f32_e32 v72, v84, v70
	v_max_f32_e32 v70, v84, v70
	v_max_f32_e32 v84, v71, v75
	v_min_f32_e32 v71, v71, v75
	v_max_f32_e32 v75, v73, v74
	v_min_f32_e32 v73, v73, v74
	v_min_f32_e32 v74, v76, v79
	v_max_f32_e32 v76, v76, v79
	v_min_f32_e32 v79, v77, v78
	v_max_f32_e32 v77, v77, v78
	v_max_f32_e32 v78, v80, v83
	v_min_f32_e32 v80, v80, v83
	v_max_f32_e32 v83, v81, v82
	v_min_f32_e32 v81, v81, v82
	v_min_f32_e32 v11, v0, v18
	v_max_f32_e32 v0, v0, v18
	v_min_f32_e32 v18, v7, v16
	v_max_f32_e32 v7, v7, v16
	v_max_f32_e32 v16, v1, v17
	v_min_f32_e32 v1, v1, v17
	v_max_f32_e32 v17, v93, v2
	v_min_f32_e32 v2, v93, v2
	v_min_f32_e32 v93, v3, v8
	v_max_f32_e32 v3, v3, v8
	v_min_f32_e32 v8, v19, v4
	v_max_f32_e32 v4, v19, v4
	v_max_f32_e32 v19, v5, v10
	v_min_f32_e32 v5, v5, v10
	v_max_f32_e32 v10, v9, v6
	v_min_f32_e32 v6, v9, v6
	v_min_f32_e32 v29, v12, v15
	v_max_f32_e32 v12, v12, v15
	v_min_f32_e32 v15, v32, v31
	v_max_f32_e32 v31, v32, v31
	v_min_f32_e32 v32, v13, v20
	v_max_f32_e32 v13, v13, v20
	v_min_f32_e32 v20, v14, v22
	v_max_f32_e32 v14, v14, v22
	v_max_f32_e32 v22, v23, v27
	v_min_f32_e32 v23, v23, v27
	v_max_f32_e32 v27, v21, v25
	v_min_f32_e32 v21, v21, v25
	v_max_f32_e32 v25, v24, v28
	v_min_f32_e32 v24, v24, v28
	v_max_f32_e32 v28, v26, v30
	v_min_f32_e32 v26, v26, v30
	v_min_f32_e32 v53, v40, v43
	v_max_f32_e32 v40, v40, v43
	v_min_f32_e32 v43, v56, v55
	v_max_f32_e32 v55, v56, v55
	v_min_f32_e32 v56, v41, v44
	v_max_f32_e32 v41, v41, v44
	v_min_f32_e32 v44, v42, v46
	v_max_f32_e32 v42, v42, v46
	v_max_f32_e32 v46, v47, v51
	v_min_f32_e32 v47, v47, v51
	v_max_f32_e32 v51, v45, v49
	v_min_f32_e32 v45, v45, v49
	v_max_f32_e32 v49, v48, v52
	v_min_f32_e32 v48, v48, v52
	v_max_f32_e32 v52, v50, v54
	v_min_f32_e32 v50, v50, v54
	v_min_f32_e32 v82, v64, v71
	v_max_f32_e32 v64, v64, v71
	v_min_f32_e32 v71, v85, v84
	v_max_f32_e32 v84, v85, v84
	v_min_f32_e32 v85, v70, v73
	v_max_f32_e32 v70, v70, v73
	v_min_f32_e32 v73, v72, v75
	v_max_f32_e32 v72, v72, v75
	v_max_f32_e32 v75, v76, v80
	v_min_f32_e32 v76, v76, v80
	v_max_f32_e32 v80, v74, v78
	v_min_f32_e32 v74, v74, v78
	v_max_f32_e32 v78, v77, v81
	v_min_f32_e32 v77, v77, v81
	v_max_f32_e32 v81, v79, v83
	v_min_f32_e32 v79, v79, v83
	v_min_f32_e32 v9, v0, v1
	v_max_f32_e32 v0, v0, v1
	v_min_f32_e32 v1, v11, v16
	v_max_f32_e32 v11, v11, v16
	v_min_f32_e32 v16, v7, v2
	v_max_f32_e32 v2, v7, v2
	v_min_f32_e32 v7, v18, v17
	v_max_f32_e32 v17, v18, v17
	v_max_f32_e32 v18, v3, v5
	v_min_f32_e32 v3, v3, v5
	v_max_f32_e32 v5, v93, v19
	v_min_f32_e32 v19, v93, v19
	v_max_f32_e32 v93, v4, v6
	v_min_f32_e32 v4, v4, v6
	v_max_f32_e32 v6, v8, v10
	v_min_f32_e32 v8, v8, v10
	v_min_f32_e32 v30, v12, v13
	v_max_f32_e32 v12, v12, v13
	v_min_f32_e32 v13, v31, v14
	v_max_f32_e32 v14, v31, v14
	v_min_f32_e32 v31, v29, v32
	v_max_f32_e32 v29, v29, v32
	v_min_f32_e32 v32, v15, v20
	v_max_f32_e32 v15, v15, v20
	v_max_f32_e32 v20, v23, v24
	v_min_f32_e32 v23, v23, v24
	v_max_f32_e32 v24, v21, v26
	v_min_f32_e32 v21, v21, v26
	v_max_f32_e32 v26, v22, v25
	v_min_f32_e32 v22, v22, v25
	v_max_f32_e32 v25, v27, v28
	v_min_f32_e32 v27, v27, v28
	v_min_f32_e32 v54, v40, v41
	v_max_f32_e32 v40, v40, v41
	v_min_f32_e32 v41, v55, v42
	v_max_f32_e32 v42, v55, v42
	v_min_f32_e32 v55, v53, v56
	v_max_f32_e32 v53, v53, v56
	v_min_f32_e32 v56, v43, v44
	v_max_f32_e32 v43, v43, v44
	v_max_f32_e32 v44, v47, v48
	v_min_f32_e32 v47, v47, v48
	v_max_f32_e32 v48, v45, v50
	v_min_f32_e32 v45, v45, v50
	v_max_f32_e32 v50, v46, v49
	v_min_f32_e32 v46, v46, v49
	v_max_f32_e32 v49, v51, v52
	v_min_f32_e32 v51, v51, v52
	v_min_f32_e32 v83, v64, v70
	v_max_f32_e32 v64, v64, v70
	v_min_f32_e32 v70, v84, v72
	v_max_f32_e32 v72, v84, v72
	v_min_f32_e32 v84, v82, v85
	v_max_f32_e32 v82, v82, v85
	v_min_f32_e32 v85, v71, v73
	v_max_f32_e32 v71, v71, v73
	v_max_f32_e32 v73, v76, v77
	v_min_f32_e32 v76, v76, v77
	v_max_f32_e32 v77, v74, v79
	v_min_f32_e32 v74, v74, v79
	v_max_f32_e32 v79, v75, v78
	v_min_f32_e32 v75, v75, v78
	v_max_f32_e32 v78, v80, v81
	v_min_f32_e32 v80, v80, v81
	v_min_f32_e32 v10, v0, v2
	v_max_f32_e32 v0, v0, v2
	v_min_f32_e32 v2, v11, v17
	v_max_f32_e32 v11, v11, v17
	v_min_f32_e32 v17, v9, v16
	v_max_f32_e32 v9, v9, v16
	v_min_f32_e32 v16, v1, v7
	v_max_f32_e32 v1, v1, v7
	v_max_f32_e32 v7, v3, v4
	v_min_f32_e32 v3, v3, v4
	v_max_f32_e32 v4, v19, v8
	v_min_f32_e32 v8, v19, v8
	v_max_f32_e32 v19, v18, v93
	v_min_f32_e32 v18, v18, v93
	v_max_f32_e32 v93, v5, v6
	v_min_f32_e32 v5, v5, v6
	v_min_f32_e32 v28, v12, v14
	v_max_f32_e32 v12, v12, v14
	v_min_f32_e32 v14, v30, v13
	v_max_f32_e32 v13, v30, v13
	v_min_f32_e32 v30, v29, v15
	v_max_f32_e32 v15, v29, v15
	v_min_f32_e32 v29, v31, v32
	v_max_f32_e32 v31, v31, v32
	v_max_f32_e32 v32, v23, v21
	v_min_f32_e32 v21, v23, v21
	v_max_f32_e32 v23, v20, v24
	v_min_f32_e32 v20, v20, v24
	v_max_f32_e32 v24, v22, v27
	v_min_f32_e32 v22, v22, v27
	v_max_f32_e32 v27, v26, v25
	v_min_f32_e32 v25, v26, v25
	v_min_f32_e32 v52, v40, v42
	v_max_f32_e32 v40, v40, v42
	v_min_f32_e32 v42, v54, v41
	v_max_f32_e32 v41, v54, v41
	v_min_f32_e32 v54, v53, v43
	v_max_f32_e32 v43, v53, v43
	v_min_f32_e32 v53, v55, v56
	v_max_f32_e32 v55, v55, v56
	v_max_f32_e32 v56, v47, v45
	v_min_f32_e32 v45, v47, v45
	v_max_f32_e32 v47, v44, v48
	v_min_f32_e32 v44, v44, v48
	v_max_f32_e32 v48, v46, v51
	v_min_f32_e32 v46, v46, v51
	v_max_f32_e32 v51, v50, v49
	v_min_f32_e32 v49, v50, v49
	v_min_f32_e32 v81, v64, v72
	v_max_f32_e32 v64, v64, v72
	v_min_f32_e32 v72, v83, v70
	v_max_f32_e32 v70, v83, v70
	v_min_f32_e32 v83, v82, v71
	v_max_f32_e32 v71, v82, v71
	v_min_f32_e32 v82, v84, v85
	v_max_f32_e32 v84, v84, v85
	v_max_f32_e32 v85, v76, v74
	v_min_f32_e32 v74, v76, v74
	v_max_f32_e32 v76, v73, v77
	v_min_f32_e32 v73, v73, v77
	v_max_f32_e32 v77, v75, v80
	v_min_f32_e32 v75, v75, v80
	v_max_f32_e32 v80, v79, v78
	v_min_f32_e32 v78, v79, v78
	v_min_f32_e32 v6, v0, v11
	v_max_f32_e32 v0, v0, v11
	v_min_f32_e32 v11, v10, v2
	v_max_f32_e32 v2, v10, v2
	v_min_f32_e32 v10, v9, v1
	v_max_f32_e32 v1, v9, v1
	v_min_f32_e32 v9, v17, v16
	v_max_f32_e32 v16, v17, v16
	v_max_f32_e32 v17, v3, v8
	v_min_f32_e32 v3, v3, v8
	v_max_f32_e32 v8, v7, v4
	v_min_f32_e32 v4, v7, v4
	v_max_f32_e32 v7, v18, v5
	v_min_f32_e32 v5, v18, v5
	v_max_f32_e32 v18, v19, v93
	v_min_f32_e32 v19, v19, v93
	v_min_f32_e32 v26, v12, v21
	v_max_f32_e32 v12, v12, v21
	v_min_f32_e32 v21, v28, v32
	v_max_f32_e32 v28, v28, v32
	v_min_f32_e32 v32, v13, v20
	v_max_f32_e32 v13, v13, v20
	v_min_f32_e32 v20, v14, v23
	v_max_f32_e32 v14, v14, v23
	v_min_f32_e32 v23, v15, v22
	v_max_f32_e32 v15, v15, v22
	v_min_f32_e32 v22, v30, v24
	v_max_f32_e32 v24, v30, v24
	v_min_f32_e32 v30, v31, v25
	v_max_f32_e32 v25, v31, v25
	v_min_f32_e32 v31, v29, v27
	v_max_f32_e32 v27, v29, v27
	v_min_f32_e32 v50, v40, v45
	v_max_f32_e32 v40, v40, v45
	v_min_f32_e32 v45, v52, v56
	v_max_f32_e32 v52, v52, v56
	v_min_f32_e32 v56, v41, v44
	v_max_f32_e32 v41, v41, v44
	v_min_f32_e32 v44, v42, v47
	v_max_f32_e32 v42, v42, v47
	v_min_f32_e32 v47, v43, v46
	v_max_f32_e32 v43, v43, v46
	v_min_f32_e32 v46, v54, v48
	v_max_f32_e32 v48, v54, v48
	v_min_f32_e32 v54, v55, v49
	v_max_f32_e32 v49, v55, v49
	v_min_f32_e32 v55, v53, v51
	v_max_f32_e32 v51, v53, v51
	v_min_f32_e32 v79, v64, v74
	v_max_f32_e32 v64, v64, v74
	v_min_f32_e32 v74, v81, v85
	v_max_f32_e32 v81, v81, v85
	v_min_f32_e32 v85, v70, v73
	v_max_f32_e32 v70, v70, v73
	v_min_f32_e32 v73, v72, v76
	v_max_f32_e32 v72, v72, v76
	v_min_f32_e32 v76, v71, v75
	v_max_f32_e32 v71, v71, v75
	v_min_f32_e32 v75, v83, v77
	v_max_f32_e32 v77, v83, v77
	v_min_f32_e32 v83, v84, v78
	v_max_f32_e32 v78, v84, v78
	v_min_f32_e32 v84, v82, v80
	v_max_f32_e32 v80, v82, v80
	v_min_f32_e32 v93, v0, v3
	v_max_f32_e32 v0, v0, v3
	v_min_f32_e32 v3, v6, v17
	v_max_f32_e32 v6, v6, v17
	v_min_f32_e32 v17, v2, v4
	v_max_f32_e32 v2, v2, v4
	v_min_f32_e32 v4, v11, v8
	v_max_f32_e32 v8, v11, v8
	v_min_f32_e32 v11, v1, v5
	v_max_f32_e32 v1, v1, v5
	v_min_f32_e32 v5, v10, v7
	v_max_f32_e32 v7, v10, v7
	v_min_f32_e32 v10, v16, v19
	v_max_f32_e32 v16, v16, v19
	v_min_f32_e32 v19, v9, v18
	v_max_f32_e32 v9, v9, v18
	v_min_f32_e32 v33, v12, v15
	v_max_f32_e32 v15, v12, v15
	v_min_f32_e32 v34, v28, v24
	v_max_f32_e32 v24, v28, v24
	v_min_f32_e32 v28, v13, v25
	v_max_f32_e32 v13, v13, v25
	v_min_f32_e32 v25, v14, v27
	v_max_f32_e32 v14, v14, v27
	v_min_f32_e32 v27, v26, v23
	v_max_f32_e32 v26, v26, v23
	v_min_f32_e32 v35, v21, v22
	v_max_f32_e32 v36, v21, v22
	v_min_f32_e32 v37, v32, v30
	v_max_f32_e32 v22, v32, v30
	v_min_f32_e32 v32, v20, v31
	v_max_f32_e32 v31, v20, v31
	v_min_f32_e32 v53, v40, v43
	v_max_f32_e32 v40, v40, v43
	v_min_f32_e32 v43, v52, v48
	v_max_f32_e32 v48, v52, v48
	v_min_f32_e32 v52, v41, v49
	v_max_f32_e32 v41, v41, v49
	v_min_f32_e32 v49, v42, v51
	v_max_f32_e32 v42, v42, v51
	v_min_f32_e32 v51, v50, v47
	v_max_f32_e32 v47, v50, v47
	v_min_f32_e32 v50, v45, v46
	v_max_f32_e32 v45, v45, v46
	v_min_f32_e32 v46, v56, v54
	v_max_f32_e32 v54, v56, v54
	v_min_f32_e32 v56, v44, v55
	v_max_f32_e32 v44, v44, v55
	v_min_f32_e32 v82, v64, v71
	v_max_f32_e32 v64, v64, v71
	v_min_f32_e32 v71, v81, v77
	v_max_f32_e32 v77, v81, v77
	v_min_f32_e32 v81, v70, v78
	v_max_f32_e32 v70, v70, v78
	v_min_f32_e32 v78, v72, v80
	v_max_f32_e32 v72, v72, v80
	v_min_f32_e32 v80, v79, v76
	v_max_f32_e32 v76, v79, v76
	v_min_f32_e32 v79, v74, v75
	v_max_f32_e32 v74, v74, v75
	v_min_f32_e32 v75, v85, v83
	v_max_f32_e32 v83, v85, v83
	v_min_f32_e32 v85, v73, v84
	v_max_f32_e32 v73, v73, v84
	v_min_f32_e32 v18, v0, v1
	v_max_f32_e32 v0, v0, v1
	v_min_f32_e32 v1, v6, v7
	v_max_f32_e32 v6, v6, v7
	v_min_f32_e32 v7, v2, v16
	v_max_f32_e32 v2, v2, v16
	v_min_f32_e32 v16, v8, v9
	v_max_f32_e32 v8, v8, v9
	v_min_f32_e32 v9, v93, v11
	v_max_f32_e32 v11, v93, v11
	v_min_f32_e32 v93, v3, v5
	v_max_f32_e32 v3, v3, v5
	v_min_f32_e32 v5, v17, v10
	v_max_f32_e32 v10, v17, v10
	v_min_f32_e32 v17, v4, v19
	v_max_f32_e32 v4, v4, v19
	v_min_f32_e32 v12, v15, v13
	v_max_f32_e32 v23, v15, v13
	v_min_f32_e32 v20, v24, v14
	v_max_f32_e32 v29, v24, v14
	v_min_f32_e32 v13, v33, v28
	v_max_f32_e32 v24, v33, v28
	v_min_f32_e32 v21, v34, v25
	v_max_f32_e32 v30, v34, v25
	v_min_f32_e32 v14, v26, v22
	v_max_f32_e32 v25, v26, v22
	v_min_f32_e32 v22, v36, v31
	v_max_f32_e32 v31, v36, v31
	v_min_f32_e32 v15, v27, v37
	v_max_f32_e32 v26, v27, v37
	v_max_f32_e32 v28, v35, v32
	v_min_f32_e32 v27, v35, v32
	v_min_f32_e32 v55, v40, v41
	v_max_f32_e32 v40, v40, v41
	v_min_f32_e32 v41, v48, v42
	v_max_f32_e32 v42, v48, v42
	v_min_f32_e32 v48, v53, v52
	v_max_f32_e32 v52, v53, v52
	v_min_f32_e32 v53, v43, v49
	v_max_f32_e32 v43, v43, v49
	v_min_f32_e32 v49, v47, v54
	v_max_f32_e32 v47, v47, v54
	v_min_f32_e32 v54, v45, v44
	v_max_f32_e32 v44, v45, v44
	v_min_f32_e32 v45, v51, v46
	v_max_f32_e32 v46, v51, v46
	v_max_f32_e32 v51, v50, v56
	v_min_f32_e32 v50, v50, v56
	v_min_f32_e32 v84, v64, v70
	v_max_f32_e32 v64, v64, v70
	v_min_f32_e32 v70, v77, v72
	v_max_f32_e32 v72, v77, v72
	v_min_f32_e32 v77, v82, v81
	v_max_f32_e32 v81, v82, v81
	v_min_f32_e32 v82, v71, v78
	v_max_f32_e32 v71, v71, v78
	v_min_f32_e32 v78, v76, v83
	v_max_f32_e32 v76, v76, v83
	v_min_f32_e32 v83, v74, v73
	v_max_f32_e32 v73, v74, v73
	v_min_f32_e32 v74, v80, v75
	v_max_f32_e32 v75, v80, v75
	v_max_f32_e32 v80, v79, v85
	v_min_f32_e32 v79, v79, v85
	v_min_f32_e32 v19, v0, v2
	v_max_f32_e32 v0, v0, v2
	v_min_f32_e32 v2, v6, v8
	v_max_f32_e32 v6, v6, v8
	v_min_f32_e32 v8, v18, v7
	v_max_f32_e32 v7, v18, v7
	v_min_f32_e32 v18, v1, v16
	v_max_f32_e32 v1, v1, v16
	v_min_f32_e32 v16, v11, v10
	v_max_f32_e32 v10, v11, v10
	v_min_f32_e32 v11, v3, v4
	v_max_f32_e32 v3, v3, v4
	v_min_f32_e32 v4, v9, v5
	v_max_f32_e32 v5, v9, v5
	v_max_f32_e32 v9, v93, v17
	v_min_f32_e32 v17, v93, v17
	v_min_f32_e32 v39, v23, v29
	v_min_f32_e32 v38, v12, v20
	v_min_f32_e32 v37, v24, v30
	v_min_f32_e32 v36, v13, v21
	v_min_f32_e32 v35, v25, v31
	v_min_f32_e32 v34, v14, v22
	v_min_f32_e32 v33, v26, v28
	v_min_f32_e32 v32, v15, v27
	v_min_f32_e32 v56, v40, v42
	v_min_f32_e32 v57, v55, v41
	v_min_f32_e32 v58, v52, v43
	v_min_f32_e32 v59, v48, v53
	v_min_f32_e32 v60, v47, v44
	v_min_f32_e32 v61, v49, v54
	v_min_f32_e32 v62, v46, v51
	v_min_f32_e32 v63, v45, v50
	v_min_f32_e32 v85, v64, v72
	v_min_f32_e32 v86, v84, v70
	v_min_f32_e32 v87, v81, v71
	v_min_f32_e32 v88, v77, v82
	v_min_f32_e32 v89, v76, v73
	v_min_f32_e32 v90, v78, v83
	v_min_f32_e32 v91, v75, v80
	v_min_f32_e32 v92, v74, v79
	v_min_f32_e32 v93, v0, v6
	v_min_f32_e32 v94, v19, v2
	v_min_f32_e32 v95, v7, v1
	v_min_f32_e32 v96, v8, v18
	v_min_f32_e32 v97, v10, v3
	v_min_f32_e32 v98, v16, v11
	v_min_f32_e32 v99, v5, v9
	v_min_f32_e32 v100, v4, v17
	v_max3_f32 v23, v23, v29, v63
	v_max3_f32 v29, v39, v45, v50
	v_max3_f32 v12, v12, v20, v62
	v_max3_f32 v20, v38, v46, v51
	v_max3_f32 v24, v24, v30, v61
	v_max3_f32 v30, v37, v49, v54
	v_max3_f32 v13, v13, v21, v60
	v_max3_f32 v21, v36, v47, v44
	v_max3_f32 v25, v25, v31, v59
	v_max3_f32 v31, v35, v48, v53
	v_max3_f32 v14, v14, v22, v58
	v_max3_f32 v22, v34, v52, v43
	v_max3_f32 v26, v26, v28, v57
	v_max3_f32 v28, v33, v55, v41
	v_max3_f32 v15, v15, v27, v56
	v_max3_f32 v27, v32, v40, v42
	v_max3_f32 v40, v64, v72, v100
	v_max3_f32 v4, v85, v4, v17
	v_max3_f32 v17, v84, v70, v99
	v_max3_f32 v5, v86, v5, v9
	v_max3_f32 v9, v81, v71, v98
	v_max3_f32 v11, v87, v16, v11
	v_max3_f32 v16, v77, v82, v97
	v_max3_f32 v3, v88, v10, v3
	v_max3_f32 v10, v76, v73, v96
	v_max3_f32 v8, v89, v8, v18
	v_max3_f32 v18, v78, v83, v95
	v_max3_f32 v1, v90, v7, v1
	v_max3_f32 v7, v75, v80, v94
	v_max3_f32 v2, v91, v19, v2
	v_max3_f32 v19, v74, v79, v93
	v_max3_f32 v0, v92, v0, v6
	v_max_f32_e32 v32, v23, v25
	v_min_f32_e32 v23, v23, v25
	v_max_f32_e32 v25, v29, v31
	v_min_f32_e32 v29, v29, v31
	v_max_f32_e32 v31, v12, v14
	v_min_f32_e32 v12, v12, v14
	v_max_f32_e32 v14, v20, v22
	v_min_f32_e32 v20, v20, v22
	v_max_f32_e32 v22, v24, v26
	v_min_f32_e32 v24, v24, v26
	v_max_f32_e32 v26, v30, v28
	v_min_f32_e32 v28, v30, v28
	v_max_f32_e32 v30, v13, v15
	v_min_f32_e32 v13, v13, v15
	v_max_f32_e32 v15, v21, v27
	v_min_f32_e32 v21, v21, v27
	v_max_f32_e32 v6, v40, v10
	v_min_f32_e32 v10, v40, v10
	v_max_f32_e32 v40, v4, v8
	v_min_f32_e32 v4, v4, v8
	v_max_f32_e32 v8, v17, v18
	v_min_f32_e32 v17, v17, v18
	v_max_f32_e32 v18, v5, v1
	v_min_f32_e32 v1, v5, v1
	v_max_f32_e32 v5, v9, v7
	v_min_f32_e32 v7, v9, v7
	v_max_f32_e32 v9, v11, v2
	v_min_f32_e32 v2, v11, v2
	v_max_f32_e32 v11, v16, v19
	v_min_f32_e32 v16, v16, v19
	v_max_f32_e32 v19, v3, v0
	v_min_f32_e32 v0, v3, v0
	v_max_f32_e32 v27, v32, v22
	v_min_f32_e32 v22, v32, v22
	v_max_f32_e32 v32, v25, v26
	v_min_f32_e32 v25, v25, v26
	v_max_f32_e32 v26, v31, v30
	v_min_f32_e32 v30, v31, v30
	v_max_f32_e32 v31, v14, v15
	v_min_f32_e32 v14, v14, v15
	v_max_f32_e32 v15, v23, v24
	v_min_f32_e32 v23, v23, v24
	v_max_f32_e32 v24, v29, v28
	v_min_f32_e32 v28, v29, v28
	v_max_f32_e32 v29, v12, v13
	v_min_f32_e32 v12, v12, v13
	v_max_f32_e32 v13, v20, v21
	v_min_f32_e32 v20, v20, v21
	v_max_f32_e32 v3, v6, v5
	v_min_f32_e32 v5, v6, v5
	v_max_f32_e32 v6, v40, v9
	v_min_f32_e32 v9, v40, v9
	v_max_f32_e32 v40, v8, v11
	v_min_f32_e32 v8, v8, v11
	v_max_f32_e32 v11, v18, v19
	v_min_f32_e32 v18, v18, v19
	v_max_f32_e32 v19, v10, v7
	v_min_f32_e32 v7, v10, v7
	v_max_f32_e32 v10, v4, v2
	v_min_f32_e32 v2, v4, v2
	v_max_f32_e32 v4, v17, v16
	v_min_f32_e32 v16, v17, v16
	v_max_f32_e32 v17, v1, v0
	v_min_f32_e32 v0, v1, v0
	v_max_f32_e32 v21, v27, v26
	v_min_f32_e32 v26, v27, v26
	v_max_f32_e32 v27, v32, v31
	v_min_f32_e32 v31, v32, v31
	v_max_f32_e32 v32, v22, v30
	v_min_f32_e32 v22, v22, v30
	v_max_f32_e32 v30, v25, v14
	v_min_f32_e32 v14, v25, v14
	v_max_f32_e32 v25, v15, v29
	v_min_f32_e32 v15, v15, v29
	v_max_f32_e32 v29, v24, v13
	v_min_f32_e32 v13, v24, v13
	v_max_f32_e32 v24, v23, v12
	v_min_f32_e32 v12, v23, v12
	v_max_f32_e32 v23, v28, v20
	v_min_f32_e32 v20, v28, v20
	v_max_f32_e32 v1, v3, v40
	v_min_f32_e32 v3, v3, v40
	v_max_f32_e32 v40, v6, v11
	v_min_f32_e32 v6, v6, v11
	v_max_f32_e32 v11, v5, v8
	v_min_f32_e32 v5, v5, v8
	v_max_f32_e32 v8, v9, v18
	v_min_f32_e32 v9, v9, v18
	v_max_f32_e32 v18, v19, v4
	v_min_f32_e32 v4, v19, v4
	v_max_f32_e32 v19, v10, v17
	v_min_f32_e32 v10, v10, v17
	v_max_f32_e32 v17, v7, v16
	v_min_f32_e32 v7, v7, v16
	v_max_f32_e32 v16, v2, v0
	v_min_f32_e32 v0, v2, v0
	v_min_f32_e32 v28, v21, v27
	v_min_f32_e32 v33, v26, v31
	v_min_f32_e32 v34, v32, v30
	v_min_f32_e32 v35, v22, v14
	v_min_f32_e32 v36, v25, v29
	v_min_f32_e32 v37, v15, v13
	v_min_f32_e32 v38, v24, v23
	v_min_f32_e32 v39, v12, v20
	v_min_f32_e32 v2, v1, v40
	v_min_f32_e32 v41, v3, v6
	v_min_f32_e32 v42, v11, v8
	v_min_f32_e32 v43, v5, v9
	v_min_f32_e32 v44, v18, v19
	v_min_f32_e32 v45, v4, v10
	v_min_f32_e32 v46, v17, v16
	v_min_f32_e32 v47, v7, v0
	v_max3_f32 v21, v21, v27, v47
	v_max3_f32 v0, v28, v7, v0
	v_max3_f32 v7, v26, v31, v46
	v_max3_f32 v16, v33, v17, v16
	v_max3_f32 v17, v32, v30, v45
	v_max3_f32 v4, v34, v4, v10
	v_max3_f32 v10, v22, v14, v44
	v_max3_f32 v14, v35, v18, v19
	v_max3_f32 v18, v25, v29, v43
	v_max3_f32 v5, v36, v5, v9
	v_max3_f32 v9, v15, v13, v42
	v_max3_f32 v8, v37, v11, v8
	v_max3_f32 v11, v24, v23, v41
	v_max3_f32 v3, v38, v3, v6
	v_max3_f32 v2, v12, v20, v2
	v_max3_f32 v1, v39, v1, v40
	v_max_f32_e32 v6, v21, v18
	v_min_f32_e32 v12, v21, v18
	v_max_f32_e32 v13, v0, v5
	v_min_f32_e32 v0, v0, v5
	v_max_f32_e32 v5, v7, v9
	v_min_f32_e32 v7, v7, v9
	v_max_f32_e32 v9, v16, v8
	v_min_f32_e32 v8, v16, v8
	v_max_f32_e32 v15, v17, v11
	v_min_f32_e32 v11, v17, v11
	v_max_f32_e32 v16, v4, v3
	v_min_f32_e32 v3, v4, v3
	v_max_f32_e32 v4, v10, v2
	v_min_f32_e32 v2, v10, v2
	v_max_f32_e32 v10, v14, v1
	v_min_f32_e32 v1, v14, v1
	v_max_f32_e32 v14, v6, v15
	v_min_f32_e32 v6, v6, v15
	v_max_f32_e32 v15, v13, v16
	v_min_f32_e32 v13, v13, v16
	v_max_f32_e32 v16, v5, v4
	v_min_f32_e32 v4, v5, v4
	v_max_f32_e32 v5, v9, v10
	v_min_f32_e32 v9, v9, v10
	v_max_f32_e32 v10, v12, v11
	v_min_f32_e32 v11, v12, v11
	v_max_f32_e32 v12, v0, v3
	v_min_f32_e32 v0, v0, v3
	v_max_f32_e32 v3, v7, v2
	v_min_f32_e32 v2, v7, v2
	v_max_f32_e32 v7, v8, v1
	v_min_f32_e32 v1, v8, v1
	v_max_f32_e32 v17, v6, v4
	v_min_f32_e32 v6, v6, v4
	v_max_f32_e32 v4, v13, v9
	v_max_f32_e32 v18, v10, v3
	v_min_f32_e32 v3, v10, v3
	v_max_f32_e32 v10, v12, v7
	v_min_f32_e32 v7, v12, v7
	v_max_f32_e32 v8, v14, v16
	v_min_f32_e32 v14, v14, v16
	v_max_f32_e32 v16, v15, v5
	v_min_f32_e32 v15, v15, v5
	v_min_f32_e32 v9, v13, v9
	v_max_f32_e32 v19, v11, v2
	v_min_f32_e32 v2, v11, v2
	v_max_f32_e32 v11, v0, v1
	v_min_f32_e32 v23, v0, v1
	v_max_f32_e32 v20, v17, v4
	v_min_f32_e32 v4, v17, v4
	v_max_f32_e32 v17, v3, v7
	v_min_f32_e32 v3, v3, v7
	v_cndmask_b32_e32 v7, v66, v67, vcc
	v_max_f32_e32 v21, v8, v16
	v_min_f32_e32 v5, v8, v16
	v_max_f32_e32 v13, v14, v15
	v_min_f32_e32 v1, v14, v15
	v_max_f32_e32 v12, v6, v9
	v_min_f32_e32 v0, v6, v9
	v_max_f32_e32 v24, v18, v10
	v_min_f32_e32 v8, v18, v10
	v_max_f32_e32 v22, v19, v11
	v_min_f32_e32 v6, v19, v11
	v_max_f32_e32 v15, v2, v23
	v_min_f32_e32 v2, v2, v23
	v_lshlrev_b32_e32 v10, 2, v7
	ds_bpermute_b32 v29, v10, v2
	ds_bpermute_b32 v16, v10, v15
	ds_bpermute_b32 v25, v10, v6
	ds_bpermute_b32 v9, v10, v22
	ds_bpermute_b32 v28, v10, v3
	ds_bpermute_b32 v14, v10, v17
	ds_bpermute_b32 v23, v10, v8
	ds_bpermute_b32 v7, v10, v24
	ds_bpermute_b32 v31, v10, v0
	ds_bpermute_b32 v19, v10, v12
	ds_bpermute_b32 v27, v10, v4
	ds_bpermute_b32 v11, v10, v20
	ds_bpermute_b32 v30, v10, v1
	ds_bpermute_b32 v18, v10, v13
	ds_bpermute_b32 v26, v10, v5
	ds_bpermute_b32 v10, v10, v21
	v_cmp_gt_u32_e32 vcc, 32, v69
	s_and_saveexec_b64 s[14:15], vcc
	s_cbranch_execz .LBB0_1686
	s_waitcnt lgkmcnt(12)
	v_max_f32_e32 v9, v9, v9
	v_max_f32_e32 v1, v1, v1
	v_max_f32_e32 v9, v1, v9
	s_waitcnt lgkmcnt(4)
	v_max_f32_e32 v1, v11, v11
	v_max_f32_e32 v3, v3, v3
	v_max_f32_e32 v29, v29, v29
	v_max_f32_e32 v21, v21, v21
	v_max_f32_e32 v28, v28, v28
	v_max_f32_e32 v20, v20, v20
	v_max_f32_e32 v25, v25, v25
	v_max_f32_e32 v13, v13, v13
	v_max_f32_e32 v23, v23, v23
	v_max_f32_e32 v12, v12, v12
	v_max_f32_e32 v16, v16, v16
	v_max_f32_e32 v5, v5, v5
	v_max_f32_e32 v14, v14, v14
	v_max_f32_e32 v4, v4, v4
	v_max_f32_e32 v11, v3, v1
	v_max_f32_e32 v1, v7, v7
	v_max_f32_e32 v0, v0, v0
	v_max_f32_e32 v21, v21, v29
	v_max_f32_e32 v29, v31, v31
	v_max_f32_e32 v24, v24, v24
	v_max_f32_e32 v20, v20, v28
	s_waitcnt lgkmcnt(3)
	v_max_f32_e32 v28, v30, v30
	v_max_f32_e32 v22, v22, v22
	v_max_f32_e32 v13, v13, v25
	v_max_f32_e32 v25, v27, v27
	v_max_f32_e32 v17, v17, v17
	v_max_f32_e32 v12, v12, v23
	s_waitcnt lgkmcnt(1)
	v_max_f32_e32 v23, v26, v26
	v_max_f32_e32 v15, v15, v15
	v_max_f32_e32 v16, v5, v16
	v_max_f32_e32 v5, v19, v19
	v_max_f32_e32 v8, v8, v8
	v_max_f32_e32 v14, v4, v14
	v_max_f32_e32 v4, v18, v18
	v_max_f32_e32 v6, v6, v6
	v_max_f32_e32 v31, v0, v1
	s_waitcnt lgkmcnt(0)
	v_max_f32_e32 v0, v10, v10
	v_max_f32_e32 v1, v2, v2
	v_max_f32_e32 v24, v24, v29
	v_max_f32_e32 v22, v22, v28
	v_max_f32_e32 v17, v17, v25
	v_max_f32_e32 v15, v15, v23
	v_max_f32_e32 v8, v8, v5
	v_max_f32_e32 v18, v6, v4
	v_max_f32_e32 v10, v1, v0
	v_min_f32_e32 v29, v21, v24
	v_min_f32_e32 v28, v20, v22
	v_min_f32_e32 v25, v13, v17
	v_min_f32_e32 v23, v12, v15
	v_min_f32_e32 v5, v16, v8
	v_min_f32_e32 v4, v14, v18
	v_min_f32_e32 v19, v9, v11
	v_min_f32_e32 v7, v31, v10
	v_min_f32_e32 v30, v29, v28
	v_min_f32_e32 v26, v25, v23
	v_min_f32_e32 v6, v5, v4
	v_min_f32_e32 v0, v19, v7
	v_min_f32_e32 v27, v30, v26
	v_min_f32_e32 v1, v6, v0
	v_max_f32_e32 v26, v30, v26
	v_max_f32_e32 v0, v6, v0
	v_min_f32_e32 v3, v27, v1
	v_max_f32_e32 v2, v27, v1
	v_min_f32_e32 v1, v26, v0
	v_max_f32_e32 v0, v26, v0
	v_max_f32_e32 v26, v29, v28
	v_max_f32_e32 v23, v25, v23
	v_max_f32_e32 v4, v5, v4
	v_max_f32_e32 v5, v19, v7
	v_min_f32_e32 v6, v26, v23
	v_min_f32_e32 v19, v4, v5
	v_min_f32_e32 v7, v6, v19
	v_max_f32_e32 v6, v6, v19
	v_max_f32_e32 v19, v26, v23
	v_max_f32_e32 v4, v4, v5
	v_min_f32_e32 v5, v19, v4
	v_max_f32_e32 v4, v19, v4
	v_max_f32_e32 v19, v21, v24
	v_max_f32_e32 v20, v20, v22
	v_max_f32_e32 v13, v13, v17
	v_max_f32_e32 v12, v12, v15
	v_max_f32_e32 v16, v16, v8
	v_max_f32_e32 v14, v14, v18
	v_max_f32_e32 v18, v9, v11
	v_max_f32_e32 v22, v31, v10
	v_min_f32_e32 v21, v19, v20
	v_min_f32_e32 v15, v13, v12
	v_min_f32_e32 v8, v16, v14
	v_min_f32_e32 v9, v18, v22
	v_min_f32_e32 v17, v21, v15
	v_min_f32_e32 v10, v8, v9
	v_min_f32_e32 v11, v17, v10
	v_max_f32_e32 v10, v17, v10
	v_max_f32_e32 v17, v19, v20
	v_max_f32_e32 v12, v13, v12
	v_max_f32_e32 v16, v16, v14
	v_max_f32_e32 v18, v18, v22
	v_max_f32_e32 v15, v21, v15
	v_max_f32_e32 v8, v8, v9
	v_min_f32_e32 v13, v17, v12
	v_min_f32_e32 v14, v16, v18
	v_max_f32_e32 v12, v17, v12
	v_max_f32_e32 v16, v16, v18
	v_min_f32_e32 v9, v15, v8
	v_max_f32_e32 v8, v15, v8
	v_min_f32_e32 v15, v13, v14
	v_max_f32_e32 v14, v13, v14
	v_min_f32_e32 v13, v12, v16
	v_max_f32_e32 v12, v12, v16
	v_or_b32_e32 v16, s16, v69
	v_lshl_add_u32 v16, v16, 6, s36
	ds_write_b128 v16, v[12:15]
	ds_write_b128 v16, v[8:11] offset:16
	ds_write_b128 v16, v[4:7] offset:32
	ds_write_b128 v16, v[0:3] offset:48
	s_branch .LBB0_1686
